# prep weight-transpose loop: both tile load pairs overlapped (wait + LDS writes of the first load deferred until the second is in flight)
# speedup vs baseline: 1.0660x; 1.0075x over previous
; __device__ __forceinline__ void tt_load(const TDesc& d, float* t, int tid) {
; #pragma unroll
;   for (int i = 0; i < 2; ++i) {
;     const int e = tid + i * NTHR, kk = e >> 4, q = e & 15, nv = d.n0 + 4 * q;
;     const int col = (d.mode == 1) ? real_col(nv) : (d.mode == 2) ? (nv & ~255) + perm256(nv & 255) : nv;
;     const float4 v = *reinterpret_cast<const float4*>(d.src + (long)(d.k0 + kk) * d.ld + col);
;     float* w = t + kk * 65 + 4 * q; w[0] = v.x; w[1] = v.y; w[2] = v.z; w[3] = v.w;
;   }
.LBB0_36:
	v_add_u32_e32 v11, s30, v15
	v_mad_i64_i32 v[24:25], s[8:9], s44, v11, 0
	v_lshl_add_u64 v[24:25], v[24:25], 2, s[16:17]
	v_ashrrev_i32_e32 v11, 31, v10
	v_lshl_add_u64 v[10:11], v[10:11], 2, v[24:25]
	global_load_dwordx4 v[24:27], v[10:11], off
	s_cmp_gt_i32 s39, 1
	s_mov_b64 s[8:9], -1
	s_cbranch_scc0 .LBB0_38
	s_mov_b64 s[8:9], 0

; __device__ __forceinline__ int real_col(int V) {
;   const int pn = V >> 8, v = V & 255;
;   if (V >= 6144) return (V & ~255) + perm256(v);
;   const int bj = v >> 7, wc = (v >> 5) & 3, n = (v >> 4) & 1, fq = (v >> 2) & 3, j = v & 3;
;   if (pn < 8) {
;     const int seg = (pn < 4) ? (bj ? 2 : 0) : (bj ? 3 : 1);
;     return seg * 512 + (pn & 3) * 128 + 32 * wc + 8 * fq + 4 * n + j;
;   }
;   if (pn < 16) {
;     const int seg = (pn - 8) >> 1;
;     return (seg == 1) ? V : (V & ~255) + perm256(v);
;   }
;   const int s = (pn - 16) >> 1, head = ((pn - 16) & 1) * 4 + wc;
;   const int d = (s == 0 || s == 3) ? (32 * bj + 8 * fq + 4 * n + j) : (32 * bj + 16 * n + 4 * fq + j);
;   return 4096 + s * 512 + head * 64 + d;
; }
; __device__ __forceinline__ void tt_load(const TDesc& d, float* t, int tid) {
; #pragma unroll
;   for (int i = 0; i < 2; ++i) {
;     const int e = tid + i * NTHR, kk = e >> 4, q = e & 15, nv = d.n0 + 4 * q;
;     const int col = (d.mode == 1) ? real_col(nv) : (d.mode == 2) ? (nv & ~255) + perm256(nv & 255) : nv;
;     const float4 v = *reinterpret_cast<const float4*>(d.src + (long)(d.k0 + kk) * d.ld + col);
;     float* w = t + kk * 65 + 4 * q; w[0] = v.x; w[1] = v.y; w[2] = v.z; w[3] = v.w;
;   }
.LBB0_42:
	v_add_u32_e32 v9, s30, v3
	v_mad_i64_i32 v[10:11], s[4:5], s44, v9, 0
	v_lshl_add_u64 v[10:11], v[10:11], 2, s[16:17]
	v_ashrrev_i32_e32 v9, 31, v8
	v_lshl_add_u64 v[8:9], v[8:9], 2, v[10:11]
	global_load_dwordx4 v[8:11], v[8:9], off
	v_cndmask_b32_e64 v20, 0, 1, s[46:47]
	v_cmp_ne_u32_e64 s[16:17], 1, v20
	s_andn2_b64 vcc, exec, s[46:47]
	s_waitcnt vmcnt(1)
	ds_write2_b32 v2, v24, v25 offset1:1
	ds_write2_b32 v2, v26, v27 offset0:2 offset1:3
	s_waitcnt vmcnt(0)
	ds_write2_b32 v4, v8, v9 offset1:1
	ds_write2_b32 v4, v10, v11 offset0:2 offset1:3
	s_cbranch_vccnz .LBB0_55
	s_ashr_i32 s39, s26, 8
	v_sub_co_u32_e64 v10, s[8:9], s39, 16
	s_cmp_lt_i32 s39, 8
	v_readfirstlane_b32 s10, v10
	s_cselect_b64 s[6:7], -1, 0
	s_lshr_b32 s49, s10, 1
	s_cmp_eq_u32 s49, 3
	s_cselect_b64 s[46:47], -1, 0
	s_and_b32 s10, s26, 0xe00
	s_cmpk_eq_i32 s10, 0xa00
	v_or_b32_e32 v9, s26, v1
	v_bitop3_b32 v8, s26, v18, v1 bitop3:0xc8
	s_cselect_b64 s[12:13], -1, 0
	s_cmp_lt_i32 s39, 4
	v_cmp_lt_i32_e64 s[4:5], s60, v9
	v_cmp_gt_u32_e64 s[14:15], 2, v10
	s_cselect_b64 vcc, -1, 0
	v_cmp_gt_u32_e64 s[10:11], s61, v8
	s_cmp_gt_i32 s63, 1
	s_mov_b64 s[44:45], -1
	s_cbranch_scc0 .LBB0_45
	s_mov_b64 s[44:45], 0

; __device__ __forceinline__ void tt_load(const TDesc& d, float* t, int tid) {
; #pragma unroll
;   for (int i = 0; i < 2; ++i) {
;     const int e = tid + i * NTHR, kk = e >> 4, q = e & 15, nv = d.n0 + 4 * q;
;     const int col = (d.mode == 1) ? real_col(nv) : (d.mode == 2) ? (nv & ~255) + perm256(nv & 255) : nv;
;     const float4 v = *reinterpret_cast<const float4*>(d.src + (long)(d.k0 + kk) * d.ld + col);
;     float* w = t + kk * 65 + 4 * q; w[0] = v.x; w[1] = v.y; w[2] = v.z; w[3] = v.w;
;   }
; __device__ __forceinline__ void phase_prep(const Params& p) {
;     ...
;     if (two) tt_load(d1, t1, tid);
.LBB0_48:
	v_add_u32_e32 v11, s38, v15
	v_mad_i64_i32 v[24:25], s[10:11], s48, v11, 0
	v_lshl_add_u64 v[24:25], v[24:25], 2, s[42:43]
	v_ashrrev_i32_e32 v11, 31, v10
	v_lshl_add_u64 v[10:11], v[10:11], 2, v[24:25]
	global_load_dwordx4 v[24:27], v[10:11], off
	s_cmp_gt_i32 s63, 1
	s_mov_b64 s[10:11], -1
	s_cbranch_scc0 .LBB0_50
	s_mov_b64 s[10:11], 0

; __device__ __forceinline__ void tt_load(const TDesc& d, float* t, int tid) {
; #pragma unroll
;   for (int i = 0; i < 2; ++i) {
;     const int e = tid + i * NTHR, kk = e >> 4, q = e & 15, nv = d.n0 + 4 * q;
;     const int col = (d.mode == 1) ? real_col(nv) : (d.mode == 2) ? (nv & ~255) + perm256(nv & 255) : nv;
;     const float4 v = *reinterpret_cast<const float4*>(d.src + (long)(d.k0 + kk) * d.ld + col);
;     float* w = t + kk * 65 + 4 * q; w[0] = v.x; w[1] = v.y; w[2] = v.z; w[3] = v.w;
;   }
.LBB0_54:
	v_add_u32_e32 v9, s38, v3
	v_mad_i64_i32 v[10:11], s[4:5], s48, v9, 0
	v_lshl_add_u64 v[10:11], v[10:11], 2, s[42:43]
	v_ashrrev_i32_e32 v9, 31, v8
	v_lshl_add_u64 v[8:9], v[8:9], 2, v[10:11]
	global_load_dwordx4 v[8:11], v[8:9], off
	v_add_u32_e32 v20, 0x4100, v4
	v_add_u32_e32 v21, 0x4108, v4
	v_add_u32_e32 v249, 0x4100, v2
	v_add_u32_e32 v250, 0x4108, v2
	s_waitcnt vmcnt(1)
	ds_write2_b32 v249, v24, v25 offset1:1
	ds_write2_b32 v250, v26, v27 offset1:1
	s_waitcnt vmcnt(0)
	ds_write2_b32 v20, v8, v9 offset1:1
	ds_write2_b32 v21, v10, v11 offset1:1
